# sgu units moved after mix_a barrier beside hand-written vectorized HGRN scan; G2 epilogue progressive vmcnt waits
# speedup vs baseline: 1.0168x; 1.0168x over previous
.LBB0_661:
	s_lshl_b32 s0, s50, 8
	s_mov_b32 s1, s68
	s_lshl_b32 s43, s50, 9
	s_lshl_b64 s[0:1], s[0:1], 2
	s_add_u32 s50, s60, s0
	s_addc_u32 s51, s61, s1
	s_add_u32 s88, s62, s0
	v_readlane_b32 s12, v254, 26
	s_addc_u32 s89, s63, s1
	v_readlane_b32 s13, v254, 27
	s_mov_b32 s100, s10
	s_branch .LBB0_673
.Lsgu_reenter:
	s_mov_b32 s10, s100
	s_sub_u32 s101, s82, 232
	s_add_u32 s0, s101, 0x200
	s_add_u32 s1, s101, 0x2f4
	s_cmp_lt_u32 s101, 12
	s_cselect_b32 s0, s0, s1
	s_cmp_lt_u32 s101, 24
	s_cselect_b32 s101, s0, 0
	s_cmpk_gt_u32 s10, 0x3ff
	s_cbranch_scc1 .LBB0_672
	v_readlane_b32 s0, v253, 63
	s_lshl_b32 s0, s0, 17
	v_readlane_b32 s1, v254, 18
	s_add_u32 s4, s1, s0
	v_readlane_b32 s0, v254, 19
	s_addc_u32 s5, s0, 0
	s_lshl_b32 s0, s10, 7
	s_add_i32 s11, s0, 0xffff0000
	s_branch .LBB0_664
.LBB0_663:
	v_or_b32_e32 v0, s7, v172
	s_add_i32 s0, s8, s43
	v_or_b32_e32 v62, s0, v0
	v_ashrrev_i32_e32 v63, 31, v62
	v_lshl_add_u64 v[62:63], v[62:63], 2, s[66:67]
	global_load_dword v65, v[62:63], off
	s_waitcnt vmcnt(16)
	v_lshlrev_b32_e32 v70, 16, v154
	v_and_b32_e32 v71, 0xffff0000, v154
	v_ashrrev_i32_e32 v171, 31, v170
	v_readlane_b32 s6, v254, 20
	v_lshlrev_b64 v[62:63], 11, v[170:171]
	v_readlane_b32 s7, v254, 21
	s_ashr_i32 s1, s0, 31
	v_ashrrev_i32_e32 v169, 31, v168
	v_lshl_add_u64 v[62:63], s[6:7], 0, v[62:63]
	v_ashrrev_i32_e32 v167, 31, v166
	v_ashrrev_i32_e32 v165, 31, v164
	s_add_i32 s10, s10, s78
	s_waitcnt vmcnt(0)
	v_add_f32_e32 v64, v158, v65
	v_mul_f32_e32 v64, v64, v70
	v_lshlrev_b32_e32 v70, 16, v150
	v_mul_f32_e32 v64, v64, v70
	v_add_f32_e32 v70, v159, v65
	v_mul_f32_e32 v70, v70, v71
	v_and_b32_e32 v71, 0xffff0000, v150
	v_mul_f32_e32 v70, v70, v71
	v_cvt_pk_bf16_f32 v72, v64, v70
	v_add_f32_e32 v64, v160, v65
	v_lshlrev_b32_e32 v70, 16, v155
	v_mul_f32_e32 v64, v64, v70
	v_lshlrev_b32_e32 v70, 16, v151
	v_mul_f32_e32 v64, v64, v70
	v_add_f32_e32 v70, v161, v65
	v_and_b32_e32 v71, 0xffff0000, v155
	v_mul_f32_e32 v70, v70, v71
	v_and_b32_e32 v71, 0xffff0000, v151
	v_mul_f32_e32 v70, v70, v71
	v_cvt_pk_bf16_f32 v73, v64, v70
	v_add_f32_e32 v64, v146, v65
	v_lshlrev_b32_e32 v70, 16, v156
	v_mul_f32_e32 v64, v64, v70
	v_lshlrev_b32_e32 v70, 16, v152
	v_mul_f32_e32 v64, v64, v70
	v_add_f32_e32 v70, v147, v65
	v_and_b32_e32 v71, 0xffff0000, v156
	v_mul_f32_e32 v70, v70, v71
	v_and_b32_e32 v71, 0xffff0000, v152
	v_mul_f32_e32 v70, v70, v71
	v_cvt_pk_bf16_f32 v74, v64, v70
	v_add_f32_e32 v64, v148, v65
	v_lshlrev_b32_e32 v70, 16, v157
	v_mul_f32_e32 v64, v64, v70
	v_lshlrev_b32_e32 v70, 16, v153
	v_mul_f32_e32 v64, v64, v70
	v_add_f32_e32 v70, v149, v65
	v_and_b32_e32 v71, 0xffff0000, v157
	v_mul_f32_e32 v70, v70, v71
	v_and_b32_e32 v71, 0xffff0000, v153
	v_mul_f32_e32 v70, v70, v71
	v_cvt_pk_bf16_f32 v75, v64, v70
	v_lshl_add_u64 v[70:71], v[62:63], 0, v[162:163]
	v_add_f32_e32 v62, v142, v65
	v_lshlrev_b32_e32 v63, 16, v134
	v_mul_f32_e32 v62, v62, v63
	v_lshlrev_b32_e32 v63, 16, v138
	v_mul_f32_e32 v62, v62, v63
	v_add_f32_e32 v63, v143, v65
	v_and_b32_e32 v64, 0xffff0000, v134
	v_mul_f32_e32 v63, v63, v64
	v_and_b32_e32 v64, 0xffff0000, v138
	v_mul_f32_e32 v63, v63, v64
	global_store_dwordx4 v[70:71], v[72:75], off
	v_cvt_pk_bf16_f32 v62, v62, v63
	v_add_f32_e32 v63, v144, v65
	v_lshlrev_b32_e32 v64, 16, v135
	v_mul_f32_e32 v63, v63, v64
	v_lshlrev_b32_e32 v64, 16, v139
	v_mul_f32_e32 v63, v63, v64
	v_add_f32_e32 v64, v145, v65
	v_and_b32_e32 v72, 0xffff0000, v135
	v_mul_f32_e32 v64, v64, v72
	v_and_b32_e32 v72, 0xffff0000, v139
	v_mul_f32_e32 v64, v64, v72
	v_cvt_pk_bf16_f32 v63, v63, v64
	v_add_f32_e32 v64, v130, v65
	v_lshlrev_b32_e32 v72, 16, v136
	v_mul_f32_e32 v64, v64, v72
	v_lshlrev_b32_e32 v72, 16, v140
	v_mul_f32_e32 v64, v64, v72
	v_add_f32_e32 v72, v131, v65
	v_and_b32_e32 v73, 0xffff0000, v136
	v_mul_f32_e32 v72, v72, v73
	v_and_b32_e32 v73, 0xffff0000, v140
	v_mul_f32_e32 v72, v72, v73
	v_cvt_pk_bf16_f32 v64, v64, v72
	v_add_f32_e32 v72, v132, v65
	v_lshlrev_b32_e32 v73, 16, v137
	v_mul_f32_e32 v72, v72, v73
	v_lshlrev_b32_e32 v73, 16, v141
	v_mul_f32_e32 v72, v72, v73
	v_add_f32_e32 v65, v133, v65
	v_and_b32_e32 v73, 0xffff0000, v137
	v_mul_f32_e32 v65, v65, v73
	v_and_b32_e32 v73, 0xffff0000, v141
	v_mul_f32_e32 v65, v65, v73
	v_cvt_pk_bf16_f32 v65, v72, v65
	global_store_dwordx4 v[70:71], v[62:65], off offset:64
	v_lshlrev_b32_e32 v71, 16, v122
	v_and_b32_e32 v72, 0xffff0000, v122
	v_lshl_add_u64 v[62:63], v[0:1], 0, s[0:1]
	v_lshl_add_u64 v[62:63], v[62:63], 2, s[66:67]
	global_load_dword v0, v[62:63], off offset:64
	v_and_b32_e32 v73, 0xffff0000, v123
	v_and_b32_e32 v74, 0xffff0000, v124
	v_lshlrev_b64 v[64:65], 11, v[168:169]
	v_lshl_add_u64 v[64:65], s[6:7], 0, v[64:65]
	v_and_b32_e32 v75, 0xffff0000, v125
	v_lshl_add_u64 v[64:65], v[64:65], 0, v[162:163]
	s_cmpk_lt_i32 s10, 0x400
	s_cbranch_scc1 .Lsgu_nx
	s_cmp_eq_u32 s101, 0
	s_cbranch_scc1 .Lsgu_nx
	s_mov_b32 s10, s101
	s_mov_b32 s101, 0
.Lsgu_nx:
	s_lshl_b32 s0, s10, 7
	s_add_i32 s11, s0, 0xffff0000
	s_cmpk_lt_i32 s10, 0x400
	s_waitcnt vmcnt(0)
	v_add_f32_e32 v70, v126, v0
	v_mul_f32_e32 v70, v70, v71
	v_lshlrev_b32_e32 v71, 16, v118
	v_mul_f32_e32 v70, v70, v71
	v_add_f32_e32 v71, v127, v0
	v_mul_f32_e32 v71, v71, v72
	v_and_b32_e32 v72, 0xffff0000, v118
	v_mul_f32_e32 v71, v71, v72
	v_cvt_pk_bf16_f32 v70, v70, v71
	v_add_f32_e32 v71, v128, v0
	v_lshlrev_b32_e32 v72, 16, v123
	v_mul_f32_e32 v71, v71, v72
	v_lshlrev_b32_e32 v72, 16, v119
	v_mul_f32_e32 v71, v71, v72
	v_add_f32_e32 v72, v129, v0
	v_mul_f32_e32 v72, v72, v73
	v_and_b32_e32 v73, 0xffff0000, v119
	v_mul_f32_e32 v72, v72, v73
	v_cvt_pk_bf16_f32 v71, v71, v72
	v_add_f32_e32 v72, v114, v0
	v_lshlrev_b32_e32 v73, 16, v124
	v_mul_f32_e32 v72, v72, v73
	v_lshlrev_b32_e32 v73, 16, v120
	v_mul_f32_e32 v72, v72, v73
	v_add_f32_e32 v73, v115, v0
	v_mul_f32_e32 v73, v73, v74
	v_and_b32_e32 v74, 0xffff0000, v120
	v_mul_f32_e32 v73, v73, v74
	v_cvt_pk_bf16_f32 v72, v72, v73
	v_add_f32_e32 v73, v116, v0
	v_lshlrev_b32_e32 v74, 16, v125
	v_mul_f32_e32 v73, v73, v74
	v_lshlrev_b32_e32 v74, 16, v121
	v_mul_f32_e32 v73, v73, v74
	v_add_f32_e32 v74, v117, v0
	v_mul_f32_e32 v74, v74, v75
	v_and_b32_e32 v75, 0xffff0000, v121
	v_mul_f32_e32 v74, v74, v75
	v_cvt_pk_bf16_f32 v73, v73, v74
	global_store_dwordx4 v[64:65], v[70:73], off
	v_and_b32_e32 v74, 0xffff0000, v104
	s_nop 0
	v_add_f32_e32 v70, v110, v0
	v_lshlrev_b32_e32 v71, 16, v102
	v_mul_f32_e32 v70, v70, v71
	v_lshlrev_b32_e32 v71, 16, v106
	v_mul_f32_e32 v70, v70, v71
	v_add_f32_e32 v71, v111, v0
	v_and_b32_e32 v72, 0xffff0000, v102
	v_mul_f32_e32 v71, v71, v72
	v_and_b32_e32 v72, 0xffff0000, v106
	v_mul_f32_e32 v71, v71, v72
	v_cvt_pk_bf16_f32 v70, v70, v71
	v_add_f32_e32 v71, v112, v0
	v_lshlrev_b32_e32 v72, 16, v103
	v_mul_f32_e32 v71, v71, v72
	v_lshlrev_b32_e32 v72, 16, v107
	v_mul_f32_e32 v71, v71, v72
	v_add_f32_e32 v72, v113, v0
	v_and_b32_e32 v73, 0xffff0000, v103
	v_mul_f32_e32 v72, v72, v73
	v_and_b32_e32 v73, 0xffff0000, v107
	v_mul_f32_e32 v72, v72, v73
	v_cvt_pk_bf16_f32 v71, v71, v72
	v_add_f32_e32 v72, v98, v0
	v_lshlrev_b32_e32 v73, 16, v104
	v_mul_f32_e32 v72, v72, v73
	v_lshlrev_b32_e32 v73, 16, v108
	v_mul_f32_e32 v72, v72, v73
	v_add_f32_e32 v73, v99, v0
	v_mul_f32_e32 v73, v73, v74
	v_and_b32_e32 v74, 0xffff0000, v108
	v_mul_f32_e32 v73, v73, v74
	v_cvt_pk_bf16_f32 v72, v72, v73
	v_add_f32_e32 v73, v100, v0
	v_lshlrev_b32_e32 v74, 16, v105
	v_mul_f32_e32 v73, v73, v74
	v_lshlrev_b32_e32 v74, 16, v109
	v_mul_f32_e32 v73, v73, v74
	v_add_f32_e32 v0, v101, v0
	v_and_b32_e32 v74, 0xffff0000, v105
	v_mul_f32_e32 v0, v0, v74
	v_and_b32_e32 v74, 0xffff0000, v109
	v_mul_f32_e32 v0, v0, v74
	v_cvt_pk_bf16_f32 v73, v73, v0
	global_store_dwordx4 v[64:65], v[70:73], off offset:64
	global_load_dword v0, v[62:63], off offset:128
	v_lshlrev_b64 v[64:65], 11, v[166:167]
	v_lshlrev_b32_e32 v70, 16, v58
	v_and_b32_e32 v58, 0xffff0000, v58
	v_lshl_add_u64 v[64:65], s[6:7], 0, v[64:65]
	s_waitcnt vmcnt(0)
	v_add_f32_e32 v66, v66, v0
	v_add_f32_e32 v67, v67, v0
	v_mul_f32_e32 v66, v66, v70
	v_lshlrev_b32_e32 v70, 16, v54
	v_mul_f32_e32 v58, v67, v58
	v_and_b32_e32 v54, 0xffff0000, v54
	v_mul_f32_e32 v66, v66, v70
	v_mul_f32_e32 v54, v58, v54
	v_cvt_pk_bf16_f32 v54, v66, v54
	v_add_f32_e32 v58, v68, v0
	v_lshlrev_b32_e32 v66, 16, v59
	v_mul_f32_e32 v58, v58, v66
	v_lshlrev_b32_e32 v66, 16, v55
	v_mul_f32_e32 v58, v58, v66
	v_add_f32_e32 v66, v69, v0
	v_and_b32_e32 v59, 0xffff0000, v59
	v_mul_f32_e32 v59, v66, v59
	v_and_b32_e32 v55, 0xffff0000, v55
	v_mul_f32_e32 v55, v59, v55
	v_cvt_pk_bf16_f32 v55, v58, v55
	v_add_f32_e32 v50, v50, v0
	v_lshlrev_b32_e32 v58, 16, v60
	v_mul_f32_e32 v50, v50, v58
	v_lshlrev_b32_e32 v58, 16, v56
	v_mul_f32_e32 v50, v50, v58
	v_add_f32_e32 v51, v51, v0
	v_and_b32_e32 v58, 0xffff0000, v60
	v_mul_f32_e32 v51, v51, v58
	v_and_b32_e32 v56, 0xffff0000, v56
	v_mul_f32_e32 v51, v51, v56
	v_cvt_pk_bf16_f32 v56, v50, v51
	v_add_f32_e32 v50, v52, v0
	v_lshlrev_b32_e32 v51, 16, v61
	v_mul_f32_e32 v50, v50, v51
	v_lshlrev_b32_e32 v51, 16, v57
	v_mul_f32_e32 v50, v50, v51
	v_add_f32_e32 v51, v53, v0
	v_and_b32_e32 v52, 0xffff0000, v61
	v_mul_f32_e32 v51, v51, v52
	v_and_b32_e32 v52, 0xffff0000, v57
	v_mul_f32_e32 v51, v51, v52
	v_add_f32_e32 v46, v46, v0
	v_lshlrev_b32_e32 v52, 16, v38
	v_add_f32_e32 v47, v47, v0
	v_and_b32_e32 v38, 0xffff0000, v38
	v_mul_f32_e32 v46, v46, v52
	v_lshlrev_b32_e32 v52, 16, v42
	v_mul_f32_e32 v38, v47, v38
	v_and_b32_e32 v42, 0xffff0000, v42
	v_cvt_pk_bf16_f32 v57, v50, v51
	v_lshl_add_u64 v[50:51], v[64:65], 0, v[162:163]
	v_mul_f32_e32 v46, v46, v52
	v_mul_f32_e32 v38, v38, v42
	global_store_dwordx4 v[50:51], v[54:57], off
	v_cvt_pk_bf16_f32 v38, v46, v38
	v_add_f32_e32 v42, v48, v0
	v_lshlrev_b32_e32 v46, 16, v39
	v_mul_f32_e32 v42, v42, v46
	v_lshlrev_b32_e32 v46, 16, v43
	v_mul_f32_e32 v42, v42, v46
	v_add_f32_e32 v46, v49, v0
	v_and_b32_e32 v39, 0xffff0000, v39
	v_mul_f32_e32 v39, v46, v39
	v_and_b32_e32 v43, 0xffff0000, v43
	v_mul_f32_e32 v39, v39, v43
	v_cvt_pk_bf16_f32 v39, v42, v39
	v_add_f32_e32 v34, v34, v0
	v_lshlrev_b32_e32 v42, 16, v40
	v_add_f32_e32 v35, v35, v0
	v_and_b32_e32 v40, 0xffff0000, v40
	v_mul_f32_e32 v34, v34, v42
	v_lshlrev_b32_e32 v42, 16, v44
	v_mul_f32_e32 v35, v35, v40
	v_and_b32_e32 v40, 0xffff0000, v44
	v_mul_f32_e32 v34, v34, v42
	v_mul_f32_e32 v35, v35, v40
	v_cvt_pk_bf16_f32 v40, v34, v35
	v_add_f32_e32 v34, v36, v0
	v_lshlrev_b32_e32 v35, 16, v41
	v_mul_f32_e32 v34, v34, v35
	v_lshlrev_b32_e32 v35, 16, v45
	v_mul_f32_e32 v34, v34, v35
	v_add_f32_e32 v0, v37, v0
	v_and_b32_e32 v35, 0xffff0000, v41
	v_mul_f32_e32 v0, v0, v35
	v_and_b32_e32 v35, 0xffff0000, v45
	v_mul_f32_e32 v0, v0, v35
	v_cvt_pk_bf16_f32 v41, v34, v0
	global_store_dwordx4 v[50:51], v[38:41], off offset:64
	global_load_dword v0, v[62:63], off offset:192
	v_lshlrev_b32_e32 v36, 16, v22
	v_and_b32_e32 v22, 0xffff0000, v22
	v_lshlrev_b64 v[34:35], 11, v[164:165]
	v_lshl_add_u64 v[34:35], s[6:7], 0, v[34:35]
	s_waitcnt vmcnt(0)
	v_add_f32_e32 v30, v30, v0
	v_add_f32_e32 v31, v31, v0
	v_mul_f32_e32 v30, v30, v36
	v_lshlrev_b32_e32 v36, 16, v18
	v_mul_f32_e32 v22, v31, v22
	v_and_b32_e32 v18, 0xffff0000, v18
	v_mul_f32_e32 v30, v30, v36
	v_mul_f32_e32 v18, v22, v18
	v_cvt_pk_bf16_f32 v18, v30, v18
	v_add_f32_e32 v22, v32, v0
	v_lshlrev_b32_e32 v30, 16, v23
	v_mul_f32_e32 v22, v22, v30
	v_lshlrev_b32_e32 v30, 16, v19
	v_mul_f32_e32 v22, v22, v30
	v_add_f32_e32 v30, v33, v0
	v_and_b32_e32 v23, 0xffff0000, v23
	v_mul_f32_e32 v23, v30, v23
	v_and_b32_e32 v19, 0xffff0000, v19
	v_mul_f32_e32 v19, v23, v19
	v_cvt_pk_bf16_f32 v19, v22, v19
	v_add_f32_e32 v22, v26, v0
	v_lshlrev_b32_e32 v23, 16, v24
	v_mul_f32_e32 v22, v22, v23
	v_lshlrev_b32_e32 v23, 16, v20
	v_mul_f32_e32 v22, v22, v23
	v_add_f32_e32 v23, v27, v0
	v_and_b32_e32 v24, 0xffff0000, v24
	v_mul_f32_e32 v23, v23, v24
	v_and_b32_e32 v20, 0xffff0000, v20
	v_mul_f32_e32 v20, v23, v20
	v_cvt_pk_bf16_f32 v20, v22, v20
	v_add_f32_e32 v22, v28, v0
	v_lshlrev_b32_e32 v23, 16, v25
	v_mul_f32_e32 v22, v22, v23
	v_lshlrev_b32_e32 v23, 16, v21
	v_mul_f32_e32 v22, v22, v23
	v_add_f32_e32 v23, v29, v0
	v_and_b32_e32 v24, 0xffff0000, v25
	v_mul_f32_e32 v23, v23, v24
	v_and_b32_e32 v21, 0xffff0000, v21
	v_mul_f32_e32 v21, v23, v21
	v_cvt_pk_bf16_f32 v21, v22, v21
	v_lshl_add_u64 v[22:23], v[34:35], 0, v[162:163]
	global_store_dwordx4 v[22:23], v[18:21], off
	v_add_f32_e32 v14, v14, v0
	v_add_f32_e32 v15, v15, v0
	v_lshlrev_b32_e32 v18, 16, v2
	v_and_b32_e32 v2, 0xffff0000, v2
	v_mul_f32_e32 v14, v14, v18
	v_lshlrev_b32_e32 v18, 16, v6
	v_mul_f32_e32 v2, v15, v2
	v_and_b32_e32 v6, 0xffff0000, v6
	v_mul_f32_e32 v14, v14, v18
	v_mul_f32_e32 v2, v2, v6
	v_cvt_pk_bf16_f32 v2, v14, v2
	v_add_f32_e32 v6, v16, v0
	v_lshlrev_b32_e32 v14, 16, v3
	v_mul_f32_e32 v6, v6, v14
	v_lshlrev_b32_e32 v14, 16, v7
	v_mul_f32_e32 v6, v6, v14
	v_add_f32_e32 v14, v17, v0
	v_and_b32_e32 v3, 0xffff0000, v3
	v_mul_f32_e32 v3, v14, v3
	v_and_b32_e32 v7, 0xffff0000, v7
	v_mul_f32_e32 v3, v3, v7
	v_cvt_pk_bf16_f32 v3, v6, v3
	v_add_f32_e32 v6, v10, v0
	v_lshlrev_b32_e32 v7, 16, v4
	v_mul_f32_e32 v6, v6, v7
	v_lshlrev_b32_e32 v7, 16, v8
	v_mul_f32_e32 v6, v6, v7
	v_add_f32_e32 v7, v11, v0
	v_and_b32_e32 v4, 0xffff0000, v4
	v_mul_f32_e32 v4, v7, v4
	v_and_b32_e32 v7, 0xffff0000, v8
	v_mul_f32_e32 v4, v4, v7
	v_cvt_pk_bf16_f32 v4, v6, v4
	v_add_f32_e32 v6, v12, v0
	v_lshlrev_b32_e32 v7, 16, v5
	v_add_f32_e32 v0, v13, v0
	v_and_b32_e32 v5, 0xffff0000, v5
	v_mul_f32_e32 v6, v6, v7
	v_lshlrev_b32_e32 v7, 16, v9
	v_mul_f32_e32 v0, v0, v5
	v_and_b32_e32 v5, 0xffff0000, v9
	v_mul_f32_e32 v6, v6, v7
	v_mul_f32_e32 v0, v0, v5
	v_cvt_pk_bf16_f32 v5, v6, v0
	global_store_dwordx4 v[22:23], v[2:5], off offset:64
	s_barrier
	s_cbranch_scc0 .LBB0_672

.LBB0_672:
	v_readlane_b32 s12, v254, 26
	v_readlane_b32 s13, v254, 27
	s_branch .Lscan_go

.LBB0_725:
	s_or_b64 exec, exec, s[0:1]
	v_readlane_b32 s4, v254, 22
	v_readlane_b32 s5, v254, 23
	s_mov_b64 s[0:1], -1
	s_and_b64 vcc, exec, s[4:5]
	s_waitcnt lgkmcnt(0)
	s_barrier
	s_cbranch_vccz .LBB0_736
	s_branch .Lsgu_reenter
.Lscan_go:
	v_readfirstlane_b32 s14, v224
	v_and_b32_e32 v234, 63, v224
	s_lshr_b32 s14, s14, 6
	s_cmp_ge_u32 s82, 232
	s_cbranch_scc1 .Lsc_done
	s_mul_i32 s14, s14, 220
	s_add_i32 s11, s14, s82
	s_sub_i32 s11, s11, 12
.Lsc_item:
	s_cmp_ge_u32 s11, 0x800
	s_cbranch_scc1 .Lsc_done
	s_and_b32 s14, s11, 15
	s_lshl_b32 s14, s14, 6
	v_add_u32_e32 v235, s14, v234
	v_lshlrev_b32_e32 v236, 3, v235
	v_and_b32_e32 v237, 15, v235
	v_lshlrev_b32_e32 v238, 10, v237
	v_lshlrev_b32_e32 v237, 4, v237
	v_lshrrev_b32_e32 v239, 4, v235
	v_lshl_add_u32 v238, v239, 2, v238
	s_lshr_b32 s14, s11, 4
	s_and_b32 s14, s14, 63
	s_lshr_b32 s16, s14, 2
	s_and_b32 s17, s14, 3
	s_add_u32 s18, s42, s16
	s_lshl_b32 s18, s18, 2
	s_add_u32 s18, s18, s17
	s_lshl_b32 s18, s18, 14
	s_cmp_ge_u32 s11, 0x400
	s_cbranch_scc1 .Lsc_sample
	s_lshl_b32 s19, s16, 8
	s_add_u32 s19, s19, s17
	s_lshl_b32 s14, s19, 13
	s_add_u32 s4, s58, 0x29280000
	s_addc_u32 s5, s59, 0
	s_add_u32 s4, s4, s14
	s_addc_u32 s5, s5, 0
	s_add_u32 s6, s58, 0x2d380000
	s_addc_u32 s7, s59, 0
	s_add_u32 s6, s6, s14
	s_addc_u32 s7, s7, 0
	s_lshl_b32 s14, s19, 8
	s_add_u32 s8, s58, 0x2f400000
	s_addc_u32 s9, s59, 0
	s_add_u32 s8, s8, s14
	s_addc_u32 s9, s9, 0
	v_mov_b32_e32 v216, 0
	v_mov_b32_e32 v217, 0
	v_mov_b32_e32 v218, 0
	v_mov_b32_e32 v219, 0
	s_mov_b32 s10, 0
.Lsc_batch:
	global_load_dwordx2 v[30:31], v236, s[4:5]
	s_add_u32 s4, s4, 0x8000
	s_addc_u32 s5, s5, 0
	global_load_dwordx4 v[98:101], v237, s[8:9]
	global_load_dwordx2 v[32:33], v236, s[4:5]
	s_add_u32 s4, s4, 0x8000
	s_addc_u32 s5, s5, 0
	global_load_dwordx4 v[102:105], v237, s[8:9] offset:1024
	global_load_dwordx2 v[34:35], v236, s[4:5]
	s_add_u32 s4, s4, 0x8000
	s_addc_u32 s5, s5, 0
	global_load_dwordx4 v[106:109], v237, s[8:9] offset:2048
	global_load_dwordx2 v[36:37], v236, s[4:5]
	s_add_u32 s4, s4, 0x8000
	s_addc_u32 s5, s5, 0
	global_load_dwordx4 v[110:113], v237, s[8:9] offset:3072
	s_add_u32 s8, s8, 0x1000
	s_addc_u32 s9, s9, 0
	global_load_dwordx2 v[38:39], v236, s[4:5]
	s_add_u32 s4, s4, 0x8000
	s_addc_u32 s5, s5, 0
	global_load_dwordx4 v[114:117], v237, s[8:9]
	global_load_dwordx2 v[40:41], v236, s[4:5]
	s_add_u32 s4, s4, 0x8000
	s_addc_u32 s5, s5, 0
	global_load_dwordx4 v[118:121], v237, s[8:9] offset:1024
	global_load_dwordx2 v[42:43], v236, s[4:5]
	s_add_u32 s4, s4, 0x8000
	s_addc_u32 s5, s5, 0
	global_load_dwordx4 v[122:125], v237, s[8:9] offset:2048
	global_load_dwordx2 v[44:45], v236, s[4:5]
	s_add_u32 s4, s4, 0x8000
	s_addc_u32 s5, s5, 0
	global_load_dwordx4 v[126:129], v237, s[8:9] offset:3072
	s_add_u32 s8, s8, 0x1000
	s_addc_u32 s9, s9, 0
	global_load_dwordx2 v[46:47], v236, s[4:5]
	s_add_u32 s4, s4, 0x8000
	s_addc_u32 s5, s5, 0
	global_load_dwordx4 v[130:133], v237, s[8:9]
	global_load_dwordx2 v[48:49], v236, s[4:5]
	s_add_u32 s4, s4, 0x8000
	s_addc_u32 s5, s5, 0
	global_load_dwordx4 v[2:5], v237, s[8:9] offset:1024
	global_load_dwordx2 v[50:51], v236, s[4:5]
	s_add_u32 s4, s4, 0x8000
	s_addc_u32 s5, s5, 0
	global_load_dwordx4 v[6:9], v237, s[8:9] offset:2048
	global_load_dwordx2 v[52:53], v236, s[4:5]
	s_add_u32 s4, s4, 0x8000
	s_addc_u32 s5, s5, 0
	global_load_dwordx4 v[10:13], v237, s[8:9] offset:3072
	s_add_u32 s8, s8, 0x1000
	s_addc_u32 s9, s9, 0
	global_load_dwordx2 v[58:59], v236, s[4:5]
	s_add_u32 s4, s4, 0x8000
	s_addc_u32 s5, s5, 0
	global_load_dwordx4 v[14:17], v237, s[8:9]
	global_load_dwordx2 v[60:61], v236, s[4:5]
	s_add_u32 s4, s4, 0x8000
	s_addc_u32 s5, s5, 0
	global_load_dwordx4 v[18:21], v237, s[8:9] offset:1024
	global_load_dwordx2 v[212:213], v236, s[4:5]
	s_add_u32 s4, s4, 0x8000
	s_addc_u32 s5, s5, 0
	global_load_dwordx4 v[22:25], v237, s[8:9] offset:2048
	global_load_dwordx2 v[214:215], v236, s[4:5]
	s_add_u32 s4, s4, 0x8000
	s_addc_u32 s5, s5, 0
	global_load_dwordx4 v[26:29], v237, s[8:9] offset:3072
	s_add_u32 s8, s8, 0x1000
	s_addc_u32 s9, s9, 0
	s_waitcnt vmcnt(30)
	v_cvt_pk_bf16_f32 v220, v216, v217
	v_cvt_pk_bf16_f32 v221, v218, v219
	v_lshlrev_b32_e32 v240, 16, v30
	v_and_b32_e32 v241, 0xffff0000, v30
	v_lshlrev_b32_e32 v242, 16, v31
	v_and_b32_e32 v243, 0xffff0000, v31
	global_store_dwordx2 v236, v[220:221], s[6:7]
	s_add_u32 s6, s6, 0x8000
	s_addc_u32 s7, s7, 0
	v_fma_f32 v216, v98, v216, v240
	v_fma_f32 v217, v99, v217, v241
	v_fma_f32 v218, v100, v218, v242
	v_fma_f32 v219, v101, v219, v243
	s_waitcnt vmcnt(29)
	v_cvt_pk_bf16_f32 v222, v216, v217
	v_cvt_pk_bf16_f32 v223, v218, v219
	v_lshlrev_b32_e32 v240, 16, v32
	v_and_b32_e32 v241, 0xffff0000, v32
	v_lshlrev_b32_e32 v242, 16, v33
	v_and_b32_e32 v243, 0xffff0000, v33
	global_store_dwordx2 v236, v[222:223], s[6:7]
	s_add_u32 s6, s6, 0x8000
	s_addc_u32 s7, s7, 0
	v_fma_f32 v216, v102, v216, v240
	v_fma_f32 v217, v103, v217, v241
	v_fma_f32 v218, v104, v218, v242
	v_fma_f32 v219, v105, v219, v243
	s_waitcnt vmcnt(28)
	v_cvt_pk_bf16_f32 v220, v216, v217
	v_cvt_pk_bf16_f32 v221, v218, v219
	v_lshlrev_b32_e32 v240, 16, v34
	v_and_b32_e32 v241, 0xffff0000, v34
	v_lshlrev_b32_e32 v242, 16, v35
	v_and_b32_e32 v243, 0xffff0000, v35
	global_store_dwordx2 v236, v[220:221], s[6:7]
	s_add_u32 s6, s6, 0x8000
	s_addc_u32 s7, s7, 0
	v_fma_f32 v216, v106, v216, v240
	v_fma_f32 v217, v107, v217, v241
	v_fma_f32 v218, v108, v218, v242
	v_fma_f32 v219, v109, v219, v243
	s_waitcnt vmcnt(27)
	v_cvt_pk_bf16_f32 v222, v216, v217
	v_cvt_pk_bf16_f32 v223, v218, v219
	v_lshlrev_b32_e32 v240, 16, v36
	v_and_b32_e32 v241, 0xffff0000, v36
	v_lshlrev_b32_e32 v242, 16, v37
	v_and_b32_e32 v243, 0xffff0000, v37
	global_store_dwordx2 v236, v[222:223], s[6:7]
	s_add_u32 s6, s6, 0x8000
	s_addc_u32 s7, s7, 0
	v_fma_f32 v216, v110, v216, v240
	v_fma_f32 v217, v111, v217, v241
	v_fma_f32 v218, v112, v218, v242
	v_fma_f32 v219, v113, v219, v243
	s_waitcnt vmcnt(26)
	v_cvt_pk_bf16_f32 v220, v216, v217
	v_cvt_pk_bf16_f32 v221, v218, v219
	v_lshlrev_b32_e32 v240, 16, v38
	v_and_b32_e32 v241, 0xffff0000, v38
	v_lshlrev_b32_e32 v242, 16, v39
	v_and_b32_e32 v243, 0xffff0000, v39
	global_store_dwordx2 v236, v[220:221], s[6:7]
	s_add_u32 s6, s6, 0x8000
	s_addc_u32 s7, s7, 0
	v_fma_f32 v216, v114, v216, v240
	v_fma_f32 v217, v115, v217, v241
	v_fma_f32 v218, v116, v218, v242
	v_fma_f32 v219, v117, v219, v243
	s_waitcnt vmcnt(25)
	v_cvt_pk_bf16_f32 v222, v216, v217
	v_cvt_pk_bf16_f32 v223, v218, v219
	v_lshlrev_b32_e32 v240, 16, v40
	v_and_b32_e32 v241, 0xffff0000, v40
	v_lshlrev_b32_e32 v242, 16, v41
	v_and_b32_e32 v243, 0xffff0000, v41
	global_store_dwordx2 v236, v[222:223], s[6:7]
	s_add_u32 s6, s6, 0x8000
	s_addc_u32 s7, s7, 0
	v_fma_f32 v216, v118, v216, v240
	v_fma_f32 v217, v119, v217, v241
	v_fma_f32 v218, v120, v218, v242
	v_fma_f32 v219, v121, v219, v243
	s_waitcnt vmcnt(24)
	v_cvt_pk_bf16_f32 v220, v216, v217
	v_cvt_pk_bf16_f32 v221, v218, v219
	v_lshlrev_b32_e32 v240, 16, v42
	v_and_b32_e32 v241, 0xffff0000, v42
	v_lshlrev_b32_e32 v242, 16, v43
	v_and_b32_e32 v243, 0xffff0000, v43
	global_store_dwordx2 v236, v[220:221], s[6:7]
	s_add_u32 s6, s6, 0x8000
	s_addc_u32 s7, s7, 0
	v_fma_f32 v216, v122, v216, v240
	v_fma_f32 v217, v123, v217, v241
	v_fma_f32 v218, v124, v218, v242
	v_fma_f32 v219, v125, v219, v243
	s_waitcnt vmcnt(23)
	v_cvt_pk_bf16_f32 v222, v216, v217
	v_cvt_pk_bf16_f32 v223, v218, v219
	v_lshlrev_b32_e32 v240, 16, v44
	v_and_b32_e32 v241, 0xffff0000, v44
	v_lshlrev_b32_e32 v242, 16, v45
	v_and_b32_e32 v243, 0xffff0000, v45
	global_store_dwordx2 v236, v[222:223], s[6:7]
	s_add_u32 s6, s6, 0x8000
	s_addc_u32 s7, s7, 0
	v_fma_f32 v216, v126, v216, v240
	v_fma_f32 v217, v127, v217, v241
	v_fma_f32 v218, v128, v218, v242
	v_fma_f32 v219, v129, v219, v243
	s_waitcnt vmcnt(22)
	v_cvt_pk_bf16_f32 v220, v216, v217
	v_cvt_pk_bf16_f32 v221, v218, v219
	v_lshlrev_b32_e32 v240, 16, v46
	v_and_b32_e32 v241, 0xffff0000, v46
	v_lshlrev_b32_e32 v242, 16, v47
	v_and_b32_e32 v243, 0xffff0000, v47
	global_store_dwordx2 v236, v[220:221], s[6:7]
	s_add_u32 s6, s6, 0x8000
	s_addc_u32 s7, s7, 0
	v_fma_f32 v216, v130, v216, v240
	v_fma_f32 v217, v131, v217, v241
	v_fma_f32 v218, v132, v218, v242
	v_fma_f32 v219, v133, v219, v243
	s_waitcnt vmcnt(21)
	v_cvt_pk_bf16_f32 v222, v216, v217
	v_cvt_pk_bf16_f32 v223, v218, v219
	v_lshlrev_b32_e32 v240, 16, v48
	v_and_b32_e32 v241, 0xffff0000, v48
	v_lshlrev_b32_e32 v242, 16, v49
	v_and_b32_e32 v243, 0xffff0000, v49
	global_store_dwordx2 v236, v[222:223], s[6:7]
	s_add_u32 s6, s6, 0x8000
	s_addc_u32 s7, s7, 0
	v_fma_f32 v216, v2, v216, v240
	v_fma_f32 v217, v3, v217, v241
	v_fma_f32 v218, v4, v218, v242
	v_fma_f32 v219, v5, v219, v243
	s_waitcnt vmcnt(20)
	v_cvt_pk_bf16_f32 v220, v216, v217
	v_cvt_pk_bf16_f32 v221, v218, v219
	v_lshlrev_b32_e32 v240, 16, v50
	v_and_b32_e32 v241, 0xffff0000, v50
	v_lshlrev_b32_e32 v242, 16, v51
	v_and_b32_e32 v243, 0xffff0000, v51
	global_store_dwordx2 v236, v[220:221], s[6:7]
	s_add_u32 s6, s6, 0x8000
	s_addc_u32 s7, s7, 0
	v_fma_f32 v216, v6, v216, v240
	v_fma_f32 v217, v7, v217, v241
	v_fma_f32 v218, v8, v218, v242
	v_fma_f32 v219, v9, v219, v243
	s_waitcnt vmcnt(19)
	v_cvt_pk_bf16_f32 v222, v216, v217
	v_cvt_pk_bf16_f32 v223, v218, v219
	v_lshlrev_b32_e32 v240, 16, v52
	v_and_b32_e32 v241, 0xffff0000, v52
	v_lshlrev_b32_e32 v242, 16, v53
	v_and_b32_e32 v243, 0xffff0000, v53
	global_store_dwordx2 v236, v[222:223], s[6:7]
	s_add_u32 s6, s6, 0x8000
	s_addc_u32 s7, s7, 0
	v_fma_f32 v216, v10, v216, v240
	v_fma_f32 v217, v11, v217, v241
	v_fma_f32 v218, v12, v218, v242
	v_fma_f32 v219, v13, v219, v243
	s_waitcnt vmcnt(18)
	v_cvt_pk_bf16_f32 v220, v216, v217
	v_cvt_pk_bf16_f32 v221, v218, v219
	v_lshlrev_b32_e32 v240, 16, v58
	v_and_b32_e32 v241, 0xffff0000, v58
	v_lshlrev_b32_e32 v242, 16, v59
	v_and_b32_e32 v243, 0xffff0000, v59
	global_store_dwordx2 v236, v[220:221], s[6:7]
	s_add_u32 s6, s6, 0x8000
	s_addc_u32 s7, s7, 0
	v_fma_f32 v216, v14, v216, v240
	v_fma_f32 v217, v15, v217, v241
	v_fma_f32 v218, v16, v218, v242
	v_fma_f32 v219, v17, v219, v243
	s_waitcnt vmcnt(17)
	v_cvt_pk_bf16_f32 v222, v216, v217
	v_cvt_pk_bf16_f32 v223, v218, v219
	v_lshlrev_b32_e32 v240, 16, v60
	v_and_b32_e32 v241, 0xffff0000, v60
	v_lshlrev_b32_e32 v242, 16, v61
	v_and_b32_e32 v243, 0xffff0000, v61
	global_store_dwordx2 v236, v[222:223], s[6:7]
	s_add_u32 s6, s6, 0x8000
	s_addc_u32 s7, s7, 0
	v_fma_f32 v216, v18, v216, v240
	v_fma_f32 v217, v19, v217, v241
	v_fma_f32 v218, v20, v218, v242
	v_fma_f32 v219, v21, v219, v243
	s_waitcnt vmcnt(16)
	v_cvt_pk_bf16_f32 v220, v216, v217
	v_cvt_pk_bf16_f32 v221, v218, v219
	v_lshlrev_b32_e32 v240, 16, v212
	v_and_b32_e32 v241, 0xffff0000, v212
	v_lshlrev_b32_e32 v242, 16, v213
	v_and_b32_e32 v243, 0xffff0000, v213
	global_store_dwordx2 v236, v[220:221], s[6:7]
	s_add_u32 s6, s6, 0x8000
	s_addc_u32 s7, s7, 0
	v_fma_f32 v216, v22, v216, v240
	v_fma_f32 v217, v23, v217, v241
	v_fma_f32 v218, v24, v218, v242
	v_fma_f32 v219, v25, v219, v243
	s_waitcnt vmcnt(15)
	v_cvt_pk_bf16_f32 v222, v216, v217
	v_cvt_pk_bf16_f32 v223, v218, v219
	v_lshlrev_b32_e32 v240, 16, v214
	v_and_b32_e32 v241, 0xffff0000, v214
	v_lshlrev_b32_e32 v242, 16, v215
	v_and_b32_e32 v243, 0xffff0000, v215
	global_store_dwordx2 v236, v[222:223], s[6:7]
	s_add_u32 s6, s6, 0x8000
	s_addc_u32 s7, s7, 0
	v_fma_f32 v216, v26, v216, v240
	v_fma_f32 v217, v27, v217, v241
	v_fma_f32 v218, v28, v218, v242
	v_fma_f32 v219, v29, v219, v243
	s_add_i32 s10, s10, 1
	s_cmp_lt_u32 s10, 4
	s_cbranch_scc1 .Lsc_batch
	s_add_u32 s20, s56, 0x10500000
	s_addc_u32 s21, s57, 0
	s_add_u32 s20, s20, s18
	s_addc_u32 s21, s21, 0
	global_store_dword v238, v216, s[20:21]
	global_store_dword v238, v217, s[20:21] offset:256
	global_store_dword v238, v218, s[20:21] offset:512
	global_store_dword v238, v219, s[20:21] offset:768
	s_branch .Lsc_next
.Lsc_sample:
	s_add_u32 s20, s22, s18
	s_addc_u32 s21, s23, 0
	global_load_dword v216, v238, s[20:21]
	global_load_dword v217, v238, s[20:21] offset:256
	global_load_dword v218, v238, s[20:21] offset:512
	global_load_dword v219, v238, s[20:21] offset:768
	s_lshl_b32 s19, s16, 2
	s_add_u32 s19, s19, s17
	s_add_u32 s19, s19, 0x1000
	s_lshl_b32 s19, s19, 13
	s_add_u32 s6, s58, 0x2d380000
	s_addc_u32 s7, s59, 0
	s_add_u32 s6, s6, s19
	s_addc_u32 s7, s7, 0
	s_waitcnt vmcnt(0)
	v_cvt_pk_bf16_f32 v220, v216, v217
	v_cvt_pk_bf16_f32 v221, v218, v219
	global_store_dwordx2 v236, v[220:221], s[6:7]
.Lsc_next:
	s_add_u32 s11, s11, 1760
	s_branch .Lsc_item
.Lsc_done:
	s_mov_b64 s[0:1], exec

.LBB0_1373:
	s_mov_b64 s[14:15], 0x9080000
	s_lshl_b32 s16, s51, 8
	v_readlane_b32 s18, v252, 0
	v_readlane_b32 s19, v252, 1
	s_add_u32 s14, s18, s14
	s_addc_u32 s15, s19, s15
	s_ashr_i32 s17, s16, 31
	s_lshl_b64 s[18:19], s[16:17], 1
	s_add_u32 s7, s14, s18
	s_addc_u32 s9, s15, s19
	s_add_u32 s18, s7, s47
	s_addc_u32 s19, s9, 0
	v_lshl_add_u32 v130, s50, 8, v234
	v_lshl_add_u64 v[132:133], s[18:19], 0, v[0:1]
	s_mov_b32 s18, 0xf7f80000
	s_mov_b32 s19, -1
	v_ashrrev_i32_e32 v131, 31, v130
	v_lshl_add_u64 v[132:133], v[132:133], 0, s[18:19]
	v_lshlrev_b64 v[242:243], 11, v[130:131]
	v_lshl_add_u64 v[134:135], v[132:133], 0, v[242:243]
	global_load_dwordx4 v[238:241], v[134:135], off
	global_load_dwordx4 v[186:189], v[134:135], off offset:256
	v_or_b32_e32 v134, 16, v130
	v_ashrrev_i32_e32 v135, 31, v134
	v_lshlrev_b64 v[222:223], 11, v[134:135]
	v_lshl_add_u64 v[134:135], v[132:133], 0, v[222:223]
	global_load_dwordx4 v[182:185], v[134:135], off
	global_load_dwordx4 v[178:181], v[134:135], off offset:256
	v_or_b32_e32 v134, 32, v130
	v_ashrrev_i32_e32 v135, 31, v134
	v_lshlrev_b64 v[220:221], 11, v[134:135]
	v_lshl_add_u64 v[134:135], v[132:133], 0, v[220:221]
	global_load_dwordx4 v[174:177], v[134:135], off
	global_load_dwordx4 v[170:173], v[134:135], off offset:256
	v_or_b32_e32 v134, 48, v130
	v_ashrrev_i32_e32 v135, 31, v134
	v_lshlrev_b64 v[218:219], 11, v[134:135]
	v_lshl_add_u64 v[134:135], v[132:133], 0, v[218:219]
	global_load_dwordx4 v[166:169], v[134:135], off
	global_load_dwordx4 v[162:165], v[134:135], off offset:256
	v_add_u32_e32 v134, 0x80, v130
	v_ashrrev_i32_e32 v135, 31, v134
	v_lshlrev_b64 v[216:217], 11, v[134:135]
	v_lshl_add_u64 v[134:135], v[132:133], 0, v[216:217]
	global_load_dwordx4 v[158:161], v[134:135], off
	global_load_dwordx4 v[154:157], v[134:135], off offset:256
	v_add_u32_e32 v134, 0x90, v130
	v_ashrrev_i32_e32 v135, 31, v134
	v_lshlrev_b64 v[214:215], 11, v[134:135]
	v_lshl_add_u64 v[134:135], v[132:133], 0, v[214:215]
	global_load_dwordx4 v[150:153], v[134:135], off
	global_load_dwordx4 v[146:149], v[134:135], off offset:256
	v_add_u32_e32 v134, 0xa0, v130
	v_add_u32_e32 v130, 0xb0, v130
	v_ashrrev_i32_e32 v135, 31, v134
	v_ashrrev_i32_e32 v131, 31, v130
	v_lshlrev_b64 v[212:213], 11, v[134:135]
	v_lshlrev_b64 v[210:211], 11, v[130:131]
	v_or_b32_e32 v244, s16, v236
	v_lshl_add_u64 v[134:135], v[132:133], 0, v[212:213]
	v_lshl_add_u64 v[130:131], v[132:133], 0, v[210:211]
	v_ashrrev_i32_e32 v245, 31, v244
	global_load_dwordx4 v[142:145], v[134:135], off
	global_load_dwordx4 v[138:141], v[134:135], off offset:256
	s_nop 0
	global_load_dwordx4 v[134:137], v[130:131], off
	s_nop 0
	global_load_dwordx4 v[130:133], v[130:131], off offset:256
	v_lshl_add_u64 v[242:243], s[14:15], 0, v[242:243]
	s_andn2_b64 vcc, exec, s[38:39]
	s_mov_b64 s[76:77], 0x21200200
	s_waitcnt vmcnt(15)
	v_lshlrev_b32_e32 v225, 16, v238
	v_fmamk_f32 v126, v225, 0x3fb504f3, v126
	v_and_b32_e32 v225, 0xffff0000, v238
	v_fmamk_f32 v127, v225, 0x3fb504f3, v127
	v_lshlrev_b32_e32 v225, 16, v239
	v_fmamk_f32 v128, v225, 0x3fb504f3, v128
	v_and_b32_e32 v225, 0xffff0000, v239
	v_fmac_f32_e32 v129, 0x3fb504f3, v225
	v_lshlrev_b32_e32 v225, 16, v240
	v_fmamk_f32 v122, v225, 0x3fb504f3, v122
	v_and_b32_e32 v225, 0xffff0000, v240
	v_fmamk_f32 v123, v225, 0x3fb504f3, v123
	v_lshlrev_b32_e32 v225, 16, v241
	v_fmamk_f32 v124, v225, 0x3fb504f3, v124
	v_and_b32_e32 v225, 0xffff0000, v241
	v_fmac_f32_e32 v125, 0x3fb504f3, v225
	v_cvt_pk_bf16_f32 v126, v126, v127
	v_cvt_pk_bf16_f32 v127, v128, v129
	v_cvt_pk_bf16_f32 v128, v122, v123
	v_lshlrev_b64 v[122:123], 1, v[244:245]
	v_cvt_pk_bf16_f32 v129, v124, v125
	v_lshl_add_u64 v[124:125], v[242:243], 0, v[122:123]
	global_store_dwordx4 v[124:125], v[126:129], off nt
	s_waitcnt vmcnt(15)
	s_nop 1
	v_lshlrev_b32_e32 v126, 16, v186
	v_fmamk_f32 v118, v126, 0x3fb504f3, v118
	v_and_b32_e32 v126, 0xffff0000, v186
	v_fmamk_f32 v119, v126, 0x3fb504f3, v119
	v_lshlrev_b32_e32 v126, 16, v187
	v_fmamk_f32 v120, v126, 0x3fb504f3, v120
	v_and_b32_e32 v126, 0xffff0000, v187
	v_fmac_f32_e32 v121, 0x3fb504f3, v126
	v_lshlrev_b32_e32 v126, 16, v188
	v_fmamk_f32 v126, v126, 0x3fb504f3, v110
	v_and_b32_e32 v110, 0xffff0000, v188
	v_fmamk_f32 v127, v110, 0x3fb504f3, v111
	v_lshlrev_b32_e32 v110, 16, v189
	v_fmamk_f32 v128, v110, 0x3fb504f3, v112
	v_and_b32_e32 v110, 0xffff0000, v189
	v_fmac_f32_e32 v113, 0x3fb504f3, v110
	v_cvt_pk_bf16_f32 v110, v118, v119
	v_cvt_pk_bf16_f32 v111, v120, v121
	v_cvt_pk_bf16_f32 v112, v126, v127
	v_cvt_pk_bf16_f32 v113, v128, v113
	global_store_dwordx4 v[124:125], v[110:113], off offset:256 nt
	s_waitcnt vmcnt(15)
	s_nop 1
	v_and_b32_e32 v113, 0xffff0000, v182
	v_fmamk_f32 v113, v113, 0x3fb504f3, v115
	v_and_b32_e32 v115, 0xffff0000, v183
	v_lshlrev_b32_e32 v112, 16, v182
	v_fmac_f32_e32 v117, 0x3fb504f3, v115
	v_lshlrev_b32_e32 v115, 16, v184
	v_fmamk_f32 v112, v112, 0x3fb504f3, v114
	v_lshlrev_b32_e32 v114, 16, v183
	v_fmamk_f32 v115, v115, 0x3fb504f3, v106
	v_and_b32_e32 v106, 0xffff0000, v184
	v_fmamk_f32 v114, v114, 0x3fb504f3, v116
	v_fmamk_f32 v116, v106, 0x3fb504f3, v107
	v_lshlrev_b32_e32 v106, 16, v185
	v_lshl_add_u64 v[110:111], s[14:15], 0, v[222:223]
	v_fmamk_f32 v118, v106, 0x3fb504f3, v108
	v_and_b32_e32 v106, 0xffff0000, v185
	v_fmac_f32_e32 v109, 0x3fb504f3, v106
	v_cvt_pk_bf16_f32 v106, v112, v113
	v_lshl_add_u64 v[110:111], v[110:111], 0, v[122:123]
	v_cvt_pk_bf16_f32 v107, v114, v117
	v_cvt_pk_bf16_f32 v108, v115, v116
	v_cvt_pk_bf16_f32 v109, v118, v109
	global_store_dwordx4 v[110:111], v[106:109], off nt
	s_waitcnt vmcnt(15)
	s_nop 1
	v_lshlrev_b32_e32 v106, 16, v178
	v_fmamk_f32 v102, v106, 0x3fb504f3, v102
	v_and_b32_e32 v106, 0xffff0000, v178
	v_fmamk_f32 v103, v106, 0x3fb504f3, v103
	v_lshlrev_b32_e32 v106, 16, v179
	v_fmamk_f32 v104, v106, 0x3fb504f3, v104
	v_and_b32_e32 v106, 0xffff0000, v179
	v_fmac_f32_e32 v105, 0x3fb504f3, v106
	v_lshlrev_b32_e32 v106, 16, v180
	v_fmamk_f32 v106, v106, 0x3fb504f3, v94
	v_and_b32_e32 v94, 0xffff0000, v180
	v_fmamk_f32 v107, v94, 0x3fb504f3, v95
	v_lshlrev_b32_e32 v94, 16, v181
	v_fmamk_f32 v108, v94, 0x3fb504f3, v96
	v_and_b32_e32 v94, 0xffff0000, v181
	v_fmac_f32_e32 v97, 0x3fb504f3, v94
	v_cvt_pk_bf16_f32 v94, v102, v103
	v_cvt_pk_bf16_f32 v95, v104, v105
	v_cvt_pk_bf16_f32 v96, v106, v107
	v_cvt_pk_bf16_f32 v97, v108, v97
	global_store_dwordx4 v[110:111], v[94:97], off offset:256 nt
	s_waitcnt vmcnt(15)
	s_nop 1
	v_and_b32_e32 v97, 0xffff0000, v174
	v_fmamk_f32 v97, v97, 0x3fb504f3, v99
	v_and_b32_e32 v99, 0xffff0000, v175
	v_lshlrev_b32_e32 v96, 16, v174
	v_fmac_f32_e32 v101, 0x3fb504f3, v99
	v_lshlrev_b32_e32 v99, 16, v176
	v_fmamk_f32 v96, v96, 0x3fb504f3, v98
	v_lshlrev_b32_e32 v98, 16, v175
	v_fmamk_f32 v99, v99, 0x3fb504f3, v90
	v_and_b32_e32 v90, 0xffff0000, v176
	v_fmamk_f32 v98, v98, 0x3fb504f3, v100
	v_fmamk_f32 v100, v90, 0x3fb504f3, v91
	v_lshlrev_b32_e32 v90, 16, v177
	v_lshl_add_u64 v[94:95], s[14:15], 0, v[220:221]
	v_fmamk_f32 v102, v90, 0x3fb504f3, v92
	v_and_b32_e32 v90, 0xffff0000, v177
	v_fmac_f32_e32 v93, 0x3fb504f3, v90
	v_cvt_pk_bf16_f32 v90, v96, v97
	v_lshl_add_u64 v[94:95], v[94:95], 0, v[122:123]
	v_cvt_pk_bf16_f32 v91, v98, v101
	v_cvt_pk_bf16_f32 v92, v99, v100
	v_cvt_pk_bf16_f32 v93, v102, v93
	global_store_dwordx4 v[94:95], v[90:93], off nt
	s_waitcnt vmcnt(15)
	s_nop 1
	v_lshlrev_b32_e32 v90, 16, v170
	v_fmamk_f32 v86, v90, 0x3fb504f3, v86
	v_and_b32_e32 v90, 0xffff0000, v170
	v_fmamk_f32 v87, v90, 0x3fb504f3, v87
	v_lshlrev_b32_e32 v90, 16, v171
	v_fmamk_f32 v88, v90, 0x3fb504f3, v88
	v_and_b32_e32 v90, 0xffff0000, v171
	v_fmac_f32_e32 v89, 0x3fb504f3, v90
	v_lshlrev_b32_e32 v90, 16, v172
	v_fmamk_f32 v90, v90, 0x3fb504f3, v78
	v_and_b32_e32 v78, 0xffff0000, v172
	v_fmamk_f32 v91, v78, 0x3fb504f3, v79
	v_lshlrev_b32_e32 v78, 16, v173
	v_fmamk_f32 v92, v78, 0x3fb504f3, v80
	v_and_b32_e32 v78, 0xffff0000, v173
	v_fmac_f32_e32 v81, 0x3fb504f3, v78
	v_cvt_pk_bf16_f32 v78, v86, v87
	v_cvt_pk_bf16_f32 v79, v88, v89
	v_cvt_pk_bf16_f32 v80, v90, v91
	v_cvt_pk_bf16_f32 v81, v92, v81
	global_store_dwordx4 v[94:95], v[78:81], off offset:256 nt
	s_waitcnt vmcnt(15)
	s_nop 1
	v_and_b32_e32 v81, 0xffff0000, v166
	v_fmamk_f32 v81, v81, 0x3fb504f3, v83
	v_and_b32_e32 v83, 0xffff0000, v167
	v_lshlrev_b32_e32 v80, 16, v166
	v_fmac_f32_e32 v85, 0x3fb504f3, v83
	v_lshlrev_b32_e32 v83, 16, v168
	v_fmamk_f32 v80, v80, 0x3fb504f3, v82
	v_lshlrev_b32_e32 v82, 16, v167
	v_fmamk_f32 v83, v83, 0x3fb504f3, v74
	v_and_b32_e32 v74, 0xffff0000, v168
	v_fmamk_f32 v82, v82, 0x3fb504f3, v84
	v_fmamk_f32 v84, v74, 0x3fb504f3, v75
	v_lshlrev_b32_e32 v74, 16, v169
	v_lshl_add_u64 v[78:79], s[14:15], 0, v[218:219]
	v_fmamk_f32 v86, v74, 0x3fb504f3, v76
	v_and_b32_e32 v74, 0xffff0000, v169
	v_fmac_f32_e32 v77, 0x3fb504f3, v74
	v_cvt_pk_bf16_f32 v74, v80, v81
	v_lshl_add_u64 v[78:79], v[78:79], 0, v[122:123]
	v_cvt_pk_bf16_f32 v75, v82, v85
	v_cvt_pk_bf16_f32 v76, v83, v84
	v_cvt_pk_bf16_f32 v77, v86, v77
	global_store_dwordx4 v[78:79], v[74:77], off nt
	s_waitcnt vmcnt(15)
	s_nop 1
	v_lshlrev_b32_e32 v74, 16, v162
	v_fmamk_f32 v70, v74, 0x3fb504f3, v70
	v_and_b32_e32 v74, 0xffff0000, v162
	v_fmamk_f32 v71, v74, 0x3fb504f3, v71
	v_lshlrev_b32_e32 v74, 16, v163
	v_fmamk_f32 v72, v74, 0x3fb504f3, v72
	v_and_b32_e32 v74, 0xffff0000, v163
	v_fmac_f32_e32 v73, 0x3fb504f3, v74
	v_lshlrev_b32_e32 v74, 16, v164
	v_fmamk_f32 v74, v74, 0x3fb504f3, v66
	v_and_b32_e32 v66, 0xffff0000, v164
	v_fmamk_f32 v75, v66, 0x3fb504f3, v67
	v_lshlrev_b32_e32 v66, 16, v165
	v_fmamk_f32 v76, v66, 0x3fb504f3, v68
	v_and_b32_e32 v66, 0xffff0000, v165
	v_fmac_f32_e32 v69, 0x3fb504f3, v66
	v_cvt_pk_bf16_f32 v66, v70, v71
	v_cvt_pk_bf16_f32 v67, v72, v73
	v_cvt_pk_bf16_f32 v68, v74, v75
	v_cvt_pk_bf16_f32 v69, v76, v69
	global_store_dwordx4 v[78:79], v[66:69], off offset:256 nt
	s_waitcnt vmcnt(15)
	s_nop 1
	v_lshlrev_b32_e32 v68, 16, v158
	v_fmamk_f32 v62, v68, 0x3fb504f3, v62
	v_and_b32_e32 v68, 0xffff0000, v158
	v_fmamk_f32 v63, v68, 0x3fb504f3, v63
	v_lshlrev_b32_e32 v68, 16, v159
	v_fmamk_f32 v64, v68, 0x3fb504f3, v64
	v_and_b32_e32 v68, 0xffff0000, v159
	v_fmac_f32_e32 v65, 0x3fb504f3, v68
	v_lshlrev_b32_e32 v68, 16, v160
	v_fmamk_f32 v68, v68, 0x3fb504f3, v58
	v_and_b32_e32 v58, 0xffff0000, v160
	v_fmamk_f32 v69, v58, 0x3fb504f3, v59
	v_lshlrev_b32_e32 v58, 16, v161
	v_lshl_add_u64 v[66:67], s[14:15], 0, v[216:217]
	v_fmamk_f32 v70, v58, 0x3fb504f3, v60
	v_and_b32_e32 v58, 0xffff0000, v161
	v_fmac_f32_e32 v61, 0x3fb504f3, v58
	v_cvt_pk_bf16_f32 v58, v62, v63
	v_lshl_add_u64 v[62:63], v[66:67], 0, v[122:123]
	v_cvt_pk_bf16_f32 v59, v64, v65
	v_cvt_pk_bf16_f32 v60, v68, v69
	v_cvt_pk_bf16_f32 v61, v70, v61
	global_store_dwordx4 v[62:63], v[58:61], off nt
	s_waitcnt vmcnt(15)
	s_nop 1
	v_lshlrev_b32_e32 v58, 16, v154
	v_fmamk_f32 v54, v58, 0x3fb504f3, v54
	v_and_b32_e32 v58, 0xffff0000, v154
	v_fmamk_f32 v55, v58, 0x3fb504f3, v55
	v_lshlrev_b32_e32 v58, 16, v155
	v_fmamk_f32 v56, v58, 0x3fb504f3, v56
	v_and_b32_e32 v58, 0xffff0000, v155
	v_fmac_f32_e32 v57, 0x3fb504f3, v58
	v_lshlrev_b32_e32 v58, 16, v156
	v_fmamk_f32 v58, v58, 0x3fb504f3, v46
	v_and_b32_e32 v46, 0xffff0000, v156
	v_fmamk_f32 v59, v46, 0x3fb504f3, v47
	v_lshlrev_b32_e32 v46, 16, v157
	v_fmamk_f32 v60, v46, 0x3fb504f3, v48
	v_and_b32_e32 v46, 0xffff0000, v157
	v_fmac_f32_e32 v49, 0x3fb504f3, v46
	v_cvt_pk_bf16_f32 v46, v54, v55
	v_cvt_pk_bf16_f32 v47, v56, v57
	v_cvt_pk_bf16_f32 v48, v58, v59
	v_cvt_pk_bf16_f32 v49, v60, v49
	global_store_dwordx4 v[62:63], v[46:49], off offset:256 nt
	s_waitcnt vmcnt(15)
	s_nop 1
	v_and_b32_e32 v49, 0xffff0000, v150
	v_fmamk_f32 v49, v49, 0x3fb504f3, v51
	v_and_b32_e32 v51, 0xffff0000, v151
	v_lshlrev_b32_e32 v48, 16, v150
	v_fmac_f32_e32 v53, 0x3fb504f3, v51
	v_lshlrev_b32_e32 v51, 16, v152
	v_fmamk_f32 v48, v48, 0x3fb504f3, v50
	v_lshlrev_b32_e32 v50, 16, v151
	v_fmamk_f32 v51, v51, 0x3fb504f3, v42
	v_and_b32_e32 v42, 0xffff0000, v152
	v_fmamk_f32 v50, v50, 0x3fb504f3, v52
	v_fmamk_f32 v52, v42, 0x3fb504f3, v43
	v_lshlrev_b32_e32 v42, 16, v153
	v_lshl_add_u64 v[46:47], s[14:15], 0, v[214:215]
	v_fmamk_f32 v54, v42, 0x3fb504f3, v44
	v_and_b32_e32 v42, 0xffff0000, v153
	v_fmac_f32_e32 v45, 0x3fb504f3, v42
	v_cvt_pk_bf16_f32 v42, v48, v49
	v_lshl_add_u64 v[46:47], v[46:47], 0, v[122:123]
	v_cvt_pk_bf16_f32 v43, v50, v53
	v_cvt_pk_bf16_f32 v44, v51, v52
	v_cvt_pk_bf16_f32 v45, v54, v45
	global_store_dwordx4 v[46:47], v[42:45], off nt
	s_waitcnt vmcnt(15)
	s_nop 1
	v_lshlrev_b32_e32 v42, 16, v146
	v_fmamk_f32 v38, v42, 0x3fb504f3, v38
	v_and_b32_e32 v42, 0xffff0000, v146
	v_fmamk_f32 v39, v42, 0x3fb504f3, v39
	v_lshlrev_b32_e32 v42, 16, v147
	v_fmamk_f32 v40, v42, 0x3fb504f3, v40
	v_and_b32_e32 v42, 0xffff0000, v147
	v_fmac_f32_e32 v41, 0x3fb504f3, v42
	v_lshlrev_b32_e32 v42, 16, v148
	v_fmamk_f32 v42, v42, 0x3fb504f3, v30
	v_and_b32_e32 v30, 0xffff0000, v148
	v_fmamk_f32 v43, v30, 0x3fb504f3, v31
	v_lshlrev_b32_e32 v30, 16, v149
	v_fmamk_f32 v44, v30, 0x3fb504f3, v32
	v_and_b32_e32 v30, 0xffff0000, v149
	v_fmac_f32_e32 v33, 0x3fb504f3, v30
	v_cvt_pk_bf16_f32 v30, v38, v39
	v_cvt_pk_bf16_f32 v31, v40, v41
	v_cvt_pk_bf16_f32 v32, v42, v43
	v_cvt_pk_bf16_f32 v33, v44, v33
	global_store_dwordx4 v[46:47], v[30:33], off offset:256 nt
	s_waitcnt vmcnt(15)
	s_nop 1
	v_and_b32_e32 v33, 0xffff0000, v142
	v_fmamk_f32 v33, v33, 0x3fb504f3, v35
	v_and_b32_e32 v35, 0xffff0000, v143
	v_lshlrev_b32_e32 v32, 16, v142
	v_fmac_f32_e32 v37, 0x3fb504f3, v35
	v_lshlrev_b32_e32 v35, 16, v144
	v_fmamk_f32 v32, v32, 0x3fb504f3, v34
	v_lshlrev_b32_e32 v34, 16, v143
	v_fmamk_f32 v35, v35, 0x3fb504f3, v26
	v_and_b32_e32 v26, 0xffff0000, v144
	v_fmamk_f32 v34, v34, 0x3fb504f3, v36
	v_fmamk_f32 v36, v26, 0x3fb504f3, v27
	v_lshlrev_b32_e32 v26, 16, v145
	v_lshl_add_u64 v[30:31], s[14:15], 0, v[212:213]
	v_fmamk_f32 v38, v26, 0x3fb504f3, v28
	v_and_b32_e32 v26, 0xffff0000, v145
	v_fmac_f32_e32 v29, 0x3fb504f3, v26
	v_cvt_pk_bf16_f32 v26, v32, v33
	v_lshl_add_u64 v[30:31], v[30:31], 0, v[122:123]
	v_cvt_pk_bf16_f32 v27, v34, v37
	v_cvt_pk_bf16_f32 v28, v35, v36
	v_cvt_pk_bf16_f32 v29, v38, v29
	global_store_dwordx4 v[30:31], v[26:29], off nt
	s_waitcnt vmcnt(15)
	s_nop 1
	v_lshlrev_b32_e32 v26, 16, v138
	v_fmamk_f32 v22, v26, 0x3fb504f3, v22
	v_and_b32_e32 v26, 0xffff0000, v138
	v_fmamk_f32 v23, v26, 0x3fb504f3, v23
	v_lshlrev_b32_e32 v26, 16, v139
	v_fmamk_f32 v24, v26, 0x3fb504f3, v24
	v_and_b32_e32 v26, 0xffff0000, v139
	v_fmac_f32_e32 v25, 0x3fb504f3, v26
	v_lshlrev_b32_e32 v26, 16, v140
	v_fmamk_f32 v26, v26, 0x3fb504f3, v14
	v_and_b32_e32 v14, 0xffff0000, v140
	v_fmamk_f32 v27, v14, 0x3fb504f3, v15
	v_lshlrev_b32_e32 v14, 16, v141
	v_fmamk_f32 v28, v14, 0x3fb504f3, v16
	v_and_b32_e32 v14, 0xffff0000, v141
	v_fmac_f32_e32 v17, 0x3fb504f3, v14
	v_cvt_pk_bf16_f32 v14, v22, v23
	v_cvt_pk_bf16_f32 v15, v24, v25
	v_cvt_pk_bf16_f32 v16, v26, v27
	v_cvt_pk_bf16_f32 v17, v28, v17
	global_store_dwordx4 v[30:31], v[14:17], off offset:256 nt
	s_waitcnt vmcnt(15)
	s_nop 1
	v_and_b32_e32 v17, 0xffff0000, v134
	v_fmamk_f32 v17, v17, 0x3fb504f3, v19
	v_and_b32_e32 v19, 0xffff0000, v135
	v_lshlrev_b32_e32 v16, 16, v134
	v_fmac_f32_e32 v21, 0x3fb504f3, v19
	v_lshlrev_b32_e32 v19, 16, v136
	v_fmamk_f32 v16, v16, 0x3fb504f3, v18
	v_lshlrev_b32_e32 v18, 16, v135
	v_fmamk_f32 v19, v19, 0x3fb504f3, v10
	v_and_b32_e32 v10, 0xffff0000, v136
	v_fmamk_f32 v18, v18, 0x3fb504f3, v20
	v_fmamk_f32 v20, v10, 0x3fb504f3, v11
	v_lshlrev_b32_e32 v10, 16, v137
	v_lshl_add_u64 v[14:15], s[14:15], 0, v[210:211]
	v_fmamk_f32 v22, v10, 0x3fb504f3, v12
	v_and_b32_e32 v10, 0xffff0000, v137
	v_fmac_f32_e32 v13, 0x3fb504f3, v10
	v_cvt_pk_bf16_f32 v10, v16, v17
	v_lshl_add_u64 v[14:15], v[14:15], 0, v[122:123]
	v_cvt_pk_bf16_f32 v11, v18, v21
	v_cvt_pk_bf16_f32 v12, v19, v20
	v_cvt_pk_bf16_f32 v13, v22, v13
	global_store_dwordx4 v[14:15], v[10:13], off nt
	s_waitcnt vmcnt(15)
	s_mov_b64 s[14:15], -1
	s_nop 0
	v_lshlrev_b32_e32 v10, 16, v130
	v_fmamk_f32 v6, v10, 0x3fb504f3, v6
	v_and_b32_e32 v10, 0xffff0000, v130
	v_fmamk_f32 v7, v10, 0x3fb504f3, v7
	v_lshlrev_b32_e32 v10, 16, v131
	v_fmamk_f32 v8, v10, 0x3fb504f3, v8
	v_and_b32_e32 v10, 0xffff0000, v131
	v_fmac_f32_e32 v9, 0x3fb504f3, v10
	v_lshlrev_b32_e32 v10, 16, v132
	v_fmamk_f32 v10, v10, 0x3fb504f3, v2
	v_and_b32_e32 v2, 0xffff0000, v132
	v_fmamk_f32 v11, v2, 0x3fb504f3, v3
	v_lshlrev_b32_e32 v2, 16, v133
	v_fmamk_f32 v12, v2, 0x3fb504f3, v4
	v_and_b32_e32 v2, 0xffff0000, v133
	v_fmac_f32_e32 v5, 0x3fb504f3, v2
	v_cvt_pk_bf16_f32 v2, v6, v7
	v_cvt_pk_bf16_f32 v3, v8, v9
	v_cvt_pk_bf16_f32 v4, v10, v11
	v_cvt_pk_bf16_f32 v5, v12, v5
	global_store_dwordx4 v[14:15], v[2:5], off offset:256 nt
	s_cbranch_vccnz .LBB0_1362
	s_andn2_b64 vcc, exec, s[0:1]
	s_cbranch_vccnz .LBB0_1361
	s_barrier
	s_branch .LBB0_1361

	.amdhsa_kernel _Z14fwd_megakernel6Params
		.amdhsa_group_segment_fixed_size 0
		.amdhsa_private_segment_fixed_size 0
		.amdhsa_kernarg_size 432
		.amdhsa_user_sgpr_count 2
		.amdhsa_user_sgpr_dispatch_ptr 0
		.amdhsa_user_sgpr_queue_ptr 0
		.amdhsa_user_sgpr_kernarg_segment_ptr 1
		.amdhsa_user_sgpr_dispatch_id 0
		.amdhsa_user_sgpr_kernarg_preload_length 0
		.amdhsa_user_sgpr_kernarg_preload_offset 0
		.amdhsa_user_sgpr_private_segment_size 0
		.amdhsa_uses_dynamic_stack 0
		.amdhsa_enable_private_segment 0
		.amdhsa_system_sgpr_workgroup_id_x 1
		.amdhsa_system_sgpr_workgroup_id_y 0
		.amdhsa_system_sgpr_workgroup_id_z 0
		.amdhsa_system_sgpr_workgroup_info 0
		.amdhsa_system_vgpr_workitem_id 2
		.amdhsa_next_free_vgpr 256
		.amdhsa_next_free_sgpr 102
		.amdhsa_accum_offset 256
		.amdhsa_reserve_vcc 1
		.amdhsa_float_round_mode_32 0
		.amdhsa_float_round_mode_16_64 0
		.amdhsa_float_denorm_mode_32 3
		.amdhsa_float_denorm_mode_16_64 3
		.amdhsa_dx10_clamp 1
		.amdhsa_ieee_mode 1
		.amdhsa_fp16_overflow 0
		.amdhsa_tg_split 0
		.amdhsa_exception_fp_ieee_invalid_op 0
		.amdhsa_exception_fp_denorm_src 0
		.amdhsa_exception_fp_ieee_div_zero 0
		.amdhsa_exception_fp_ieee_overflow 0
		.amdhsa_exception_fp_ieee_underflow 0
		.amdhsa_exception_fp_ieee_inexact 0
		.amdhsa_exception_int_div_zero 0
	.end_amdhsa_kernel

amdhsa.kernels:
  - .agpr_count:     0
    .args:
      - .offset:         0
        .size:           176
        .value_kind:     by_value
      - .offset:         176
        .size:           4
        .value_kind:     hidden_block_count_x
      - .offset:         180
        .size:           4
        .value_kind:     hidden_block_count_y
      - .offset:         184
        .size:           4
        .value_kind:     hidden_block_count_z
      - .offset:         188
        .size:           2
        .value_kind:     hidden_group_size_x
      - .offset:         190
        .size:           2
        .value_kind:     hidden_group_size_y
      - .offset:         192
        .size:           2
        .value_kind:     hidden_group_size_z
      - .offset:         194
        .size:           2
        .value_kind:     hidden_remainder_x
      - .offset:         196
        .size:           2
        .value_kind:     hidden_remainder_y
      - .offset:         198
        .size:           2
        .value_kind:     hidden_remainder_z
      - .offset:         216
        .size:           8
        .value_kind:     hidden_global_offset_x
      - .offset:         224
        .size:           8
        .value_kind:     hidden_global_offset_y
      - .offset:         232
        .size:           8
        .value_kind:     hidden_global_offset_z
      - .offset:         240
        .size:           2
        .value_kind:     hidden_grid_dims
      - .offset:         264
        .size:           8
        .value_kind:     hidden_multigrid_sync_arg
      - .offset:         296
        .size:           4
        .value_kind:     hidden_dynamic_lds_size
    .group_segment_fixed_size: 0
    .kernarg_segment_align: 8
    .kernarg_segment_size: 432
    .language:       OpenCL C
    .language_version:
      - 2
      - 0
    .max_flat_workgroup_size: 512
    .name:           _Z14fwd_megakernel6Params
    .private_segment_fixed_size: 0
    .sgpr_count:     108
    .sgpr_spill_count: 209
    .symbol:         _Z14fwd_megakernel6Params.kd
    .uniform_work_group_size: 1
    .uses_dynamic_stack: false
    .vgpr_count:     256
    .vgpr_spill_count: 0
    .wavefront_size: 64
